# grid barrier: XCD leaders no longer bump (and wait on) their per-XCD generation word, which nobody polls since waiters read the top-level word; on top of v27
# baseline (speedup 1.0000x reference)
; DI unsigned xb_ld(unsigned* p)              { return __hip_atomic_load(p, __ATOMIC_RELAXED, __HIP_MEMORY_SCOPE_AGENT); }
; DI unsigned xb_add(unsigned* p, unsigned v) { return __hip_atomic_fetch_add(p, v, __ATOMIC_RELAXED, __HIP_MEMORY_SCOPE_AGENT); }
; #define XB_SPIN(cond, bar) do { unsigned _sp = 0; while (cond) { __builtin_amdgcn_s_sleep(1); \
;     if ((++_sp & 255u) == 0u) { if (xb_ld(&(bar)[XB_TMO])) break; if (_sp > XB_SPIN_CAP) { atomicAdd(&(bar)[XB_TMO], 1u); break; } } } } while (0)
; DI void xcd_barrier(unsigned* bar, volatile LAS unsigned* st, bool leader) {
;     ...
;         const unsigned old = xb_add(&bar[XB_XSUB(x)], 1u);
;         const unsigned gen = old / nloc;
;         if (old + 1u == (gen + 1u) * nloc) {
;             __builtin_amdgcn_fence(__ATOMIC_RELEASE, "agent");
;             asm volatile("s_waitcnt vmcnt(0)" ::: "memory");
;             const unsigned og = xb_add(&bar[XB_TOP], 1u);
;             const unsigned tg = og / nx;
;             if (og + 1u == (tg + 1u) * nx) xb_add(&bar[XB_TOPGEN], 1u);
;             else XB_SPIN(xb_ld(&bar[XB_TOPGEN]) == tg, bar);
;             __builtin_amdgcn_fence(__ATOMIC_ACQUIRE, "agent");
;             xb_add(&bar[XB_XGEN(x)], 1u);
;             asm volatile("s_waitcnt vmcnt(0)" ::: "memory");
.LBB0_226:
	s_or_b64 exec, exec, s[2:3]
	s_mov_b64 s[2:3], exec
	v_mbcnt_lo_u32_b32 v0, s2, 0
	v_mbcnt_hi_u32_b32 v0, s3, v0
	v_cmp_eq_u32_e32 vcc, 0, v0
	s_waitcnt vmcnt(0)
	buffer_inv sc1
	s_and_saveexec_b64 s[6:7], vcc
	s_cbranch_execz .LBB0_228
	s_bcnt1_i32_b64 s2, s[2:3]
	v_mov_b32_e32 v0, 0x2000
	v_mov_b32_e32 v1, s2
.LBB0_228:
	s_or_b64 exec, exec, s[6:7]
	s_waitcnt vmcnt(0)

; DI unsigned xb_ld(unsigned* p)              { return __hip_atomic_load(p, __ATOMIC_RELAXED, __HIP_MEMORY_SCOPE_AGENT); }
; DI unsigned xb_add(unsigned* p, unsigned v) { return __hip_atomic_fetch_add(p, v, __ATOMIC_RELAXED, __HIP_MEMORY_SCOPE_AGENT); }
; #define XB_SPIN(cond, bar) do { unsigned _sp = 0; while (cond) { __builtin_amdgcn_s_sleep(1); \
;     if ((++_sp & 255u) == 0u) { if (xb_ld(&(bar)[XB_TMO])) break; if (_sp > XB_SPIN_CAP) { atomicAdd(&(bar)[XB_TMO], 1u); break; } } } } while (0)
; DI void xcd_barrier(unsigned* bar, volatile LAS unsigned* st, bool leader) {
;     ...
;             const unsigned og = xb_add(&bar[XB_TOP], 1u);
;             const unsigned tg = og / nx;
;             if (og + 1u == (tg + 1u) * nx) xb_add(&bar[XB_TOPGEN], 1u);
;             else XB_SPIN(xb_ld(&bar[XB_TOPGEN]) == tg, bar);
;             __builtin_amdgcn_fence(__ATOMIC_ACQUIRE, "agent");
;             xb_add(&bar[XB_XGEN(x)], 1u);
;             asm volatile("s_waitcnt vmcnt(0)" ::: "memory");
.LBB0_331:
	s_or_b64 exec, exec, s[2:3]
	s_mov_b64 s[2:3], exec
	v_mbcnt_lo_u32_b32 v0, s2, 0
	v_mbcnt_hi_u32_b32 v0, s3, v0
	v_cmp_eq_u32_e32 vcc, 0, v0
	s_waitcnt vmcnt(0)
	buffer_inv sc1
	s_and_saveexec_b64 s[6:7], vcc
	s_cbranch_execz .LBB0_333
	s_bcnt1_i32_b64 s2, s[2:3]
	v_mov_b32_e32 v0, 0x2000
	v_mov_b32_e32 v1, s2
.LBB0_333:
	s_or_b64 exec, exec, s[6:7]
	s_waitcnt vmcnt(0)

; DI unsigned xb_ld(unsigned* p)              { return __hip_atomic_load(p, __ATOMIC_RELAXED, __HIP_MEMORY_SCOPE_AGENT); }
; DI unsigned xb_add(unsigned* p, unsigned v) { return __hip_atomic_fetch_add(p, v, __ATOMIC_RELAXED, __HIP_MEMORY_SCOPE_AGENT); }
; #define XB_SPIN(cond, bar) do { unsigned _sp = 0; while (cond) { __builtin_amdgcn_s_sleep(1); \
;     if ((++_sp & 255u) == 0u) { if (xb_ld(&(bar)[XB_TMO])) break; if (_sp > XB_SPIN_CAP) { atomicAdd(&(bar)[XB_TMO], 1u); break; } } } } while (0)
; DI void xcd_barrier(unsigned* bar, volatile LAS unsigned* st, bool leader) {
;     ...
;             const unsigned og = xb_add(&bar[XB_TOP], 1u);
;             const unsigned tg = og / nx;
;             if (og + 1u == (tg + 1u) * nx) xb_add(&bar[XB_TOPGEN], 1u);
;             else XB_SPIN(xb_ld(&bar[XB_TOPGEN]) == tg, bar);
;             __builtin_amdgcn_fence(__ATOMIC_ACQUIRE, "agent");
;             xb_add(&bar[XB_XGEN(x)], 1u);
;             asm volatile("s_waitcnt vmcnt(0)" ::: "memory");
.LBB0_648:
	s_or_b64 exec, exec, s[2:3]
	s_mov_b64 s[2:3], exec
	v_mbcnt_lo_u32_b32 v0, s2, 0
	v_mbcnt_hi_u32_b32 v0, s3, v0
	v_cmp_eq_u32_e32 vcc, 0, v0
	s_waitcnt vmcnt(0)
	buffer_inv sc1
	s_and_saveexec_b64 s[6:7], vcc
	s_cbranch_execz .LBB0_650
	s_bcnt1_i32_b64 s2, s[2:3]
	v_mov_b32_e32 v0, s2
	v_mov_b32_e32 v1, 0x2000
.LBB0_650:
	s_or_b64 exec, exec, s[6:7]
	s_waitcnt vmcnt(0)

; DI unsigned xb_ld(unsigned* p)              { return __hip_atomic_load(p, __ATOMIC_RELAXED, __HIP_MEMORY_SCOPE_AGENT); }
; DI unsigned xb_add(unsigned* p, unsigned v) { return __hip_atomic_fetch_add(p, v, __ATOMIC_RELAXED, __HIP_MEMORY_SCOPE_AGENT); }
; #define XB_SPIN(cond, bar) do { unsigned _sp = 0; while (cond) { __builtin_amdgcn_s_sleep(1); \
;     if ((++_sp & 255u) == 0u) { if (xb_ld(&(bar)[XB_TMO])) break; if (_sp > XB_SPIN_CAP) { atomicAdd(&(bar)[XB_TMO], 1u); break; } } } } while (0)
; DI void xcd_barrier(unsigned* bar, volatile LAS unsigned* st, bool leader) {
;     ...
;             const unsigned og = xb_add(&bar[XB_TOP], 1u);
;             const unsigned tg = og / nx;
;             if (og + 1u == (tg + 1u) * nx) xb_add(&bar[XB_TOPGEN], 1u);
;             else XB_SPIN(xb_ld(&bar[XB_TOPGEN]) == tg, bar);
;             __builtin_amdgcn_fence(__ATOMIC_ACQUIRE, "agent");
;             xb_add(&bar[XB_XGEN(x)], 1u);
;             asm volatile("s_waitcnt vmcnt(0)" ::: "memory");
.LBB0_883:
	s_or_b64 exec, exec, s[2:3]
	s_mov_b64 s[2:3], exec
	v_mbcnt_lo_u32_b32 v0, s2, 0
	v_mbcnt_hi_u32_b32 v0, s3, v0
	v_cmp_eq_u32_e32 vcc, 0, v0
	s_waitcnt vmcnt(0)
	buffer_inv sc1
	s_and_saveexec_b64 s[6:7], vcc
	s_cbranch_execz .LBB0_885
	s_bcnt1_i32_b64 s2, s[2:3]
	v_mov_b32_e32 v0, s2
	v_mov_b32_e32 v1, 0x2000
.LBB0_885:
	s_or_b64 exec, exec, s[6:7]
	s_waitcnt vmcnt(0)

; DI unsigned xb_ld(unsigned* p)              { return __hip_atomic_load(p, __ATOMIC_RELAXED, __HIP_MEMORY_SCOPE_AGENT); }
; DI unsigned xb_add(unsigned* p, unsigned v) { return __hip_atomic_fetch_add(p, v, __ATOMIC_RELAXED, __HIP_MEMORY_SCOPE_AGENT); }
; #define XB_SPIN(cond, bar) do { unsigned _sp = 0; while (cond) { __builtin_amdgcn_s_sleep(1); \
;     if ((++_sp & 255u) == 0u) { if (xb_ld(&(bar)[XB_TMO])) break; if (_sp > XB_SPIN_CAP) { atomicAdd(&(bar)[XB_TMO], 1u); break; } } } } while (0)
; DI void xcd_barrier(unsigned* bar, volatile LAS unsigned* st, bool leader) {
;     ...
;             const unsigned og = xb_add(&bar[XB_TOP], 1u);
;             const unsigned tg = og / nx;
;             if (og + 1u == (tg + 1u) * nx) xb_add(&bar[XB_TOPGEN], 1u);
;             else XB_SPIN(xb_ld(&bar[XB_TOPGEN]) == tg, bar);
;             __builtin_amdgcn_fence(__ATOMIC_ACQUIRE, "agent");
;             xb_add(&bar[XB_XGEN(x)], 1u);
;             asm volatile("s_waitcnt vmcnt(0)" ::: "memory");
.LBB0_1069:
	s_or_b64 exec, exec, s[2:3]
	s_mov_b64 s[2:3], exec
	v_mbcnt_lo_u32_b32 v0, s2, 0
	v_mbcnt_hi_u32_b32 v0, s3, v0
	v_cmp_eq_u32_e32 vcc, 0, v0
	s_waitcnt vmcnt(0)
	buffer_inv sc1
	s_and_saveexec_b64 s[6:7], vcc
	s_cbranch_execz .LBB0_1071
	s_bcnt1_i32_b64 s2, s[2:3]
	v_mov_b32_e32 v0, s2
	v_mov_b32_e32 v1, 0x2000
.LBB0_1071:
	s_or_b64 exec, exec, s[6:7]
	s_waitcnt vmcnt(0)

; DI unsigned xb_ld(unsigned* p)              { return __hip_atomic_load(p, __ATOMIC_RELAXED, __HIP_MEMORY_SCOPE_AGENT); }
; DI unsigned xb_add(unsigned* p, unsigned v) { return __hip_atomic_fetch_add(p, v, __ATOMIC_RELAXED, __HIP_MEMORY_SCOPE_AGENT); }
; #define XB_SPIN(cond, bar) do { unsigned _sp = 0; while (cond) { __builtin_amdgcn_s_sleep(1); \
;     if ((++_sp & 255u) == 0u) { if (xb_ld(&(bar)[XB_TMO])) break; if (_sp > XB_SPIN_CAP) { atomicAdd(&(bar)[XB_TMO], 1u); break; } } } } while (0)
; DI void xcd_barrier(unsigned* bar, volatile LAS unsigned* st, bool leader) {
;     ...
;             const unsigned og = xb_add(&bar[XB_TOP], 1u);
;             const unsigned tg = og / nx;
;             if (og + 1u == (tg + 1u) * nx) xb_add(&bar[XB_TOPGEN], 1u);
;             else XB_SPIN(xb_ld(&bar[XB_TOPGEN]) == tg, bar);
;             __builtin_amdgcn_fence(__ATOMIC_ACQUIRE, "agent");
;             xb_add(&bar[XB_XGEN(x)], 1u);
;             asm volatile("s_waitcnt vmcnt(0)" ::: "memory");
.LBB0_1471:
	s_or_b64 exec, exec, s[2:3]
	s_mov_b64 s[2:3], exec
	v_mbcnt_lo_u32_b32 v0, s2, 0
	v_mbcnt_hi_u32_b32 v0, s3, v0
	v_cmp_eq_u32_e32 vcc, 0, v0
	s_waitcnt vmcnt(0)
	buffer_inv sc1
	s_and_saveexec_b64 s[6:7], vcc
	s_cbranch_execz .LBB0_1473
	s_bcnt1_i32_b64 s2, s[2:3]
	v_mov_b32_e32 v0, s2
	v_mov_b32_e32 v1, 0x2000
.LBB0_1473:
	s_or_b64 exec, exec, s[6:7]
	s_waitcnt vmcnt(0)

; DI unsigned xb_ld(unsigned* p)              { return __hip_atomic_load(p, __ATOMIC_RELAXED, __HIP_MEMORY_SCOPE_AGENT); }
; DI unsigned xb_add(unsigned* p, unsigned v) { return __hip_atomic_fetch_add(p, v, __ATOMIC_RELAXED, __HIP_MEMORY_SCOPE_AGENT); }
; #define XB_SPIN(cond, bar) do { unsigned _sp = 0; while (cond) { __builtin_amdgcn_s_sleep(1); \
;     if ((++_sp & 255u) == 0u) { if (xb_ld(&(bar)[XB_TMO])) break; if (_sp > XB_SPIN_CAP) { atomicAdd(&(bar)[XB_TMO], 1u); break; } } } } while (0)
; DI void xcd_barrier(unsigned* bar, volatile LAS unsigned* st, bool leader) {
;     ...
;             const unsigned og = xb_add(&bar[XB_TOP], 1u);
;             const unsigned tg = og / nx;
;             if (og + 1u == (tg + 1u) * nx) xb_add(&bar[XB_TOPGEN], 1u);
;             else XB_SPIN(xb_ld(&bar[XB_TOPGEN]) == tg, bar);
;             __builtin_amdgcn_fence(__ATOMIC_ACQUIRE, "agent");
;             xb_add(&bar[XB_XGEN(x)], 1u);
;             asm volatile("s_waitcnt vmcnt(0)" ::: "memory");
.LBB0_2204:
	s_bcnt1_i32_b64 s2, s[2:3]
	v_mov_b32_e32 v0, s2
	v_mov_b32_e32 v1, 0x2000
	s_getpc_b64 s[98:99]
